# MLA prep3a fast path: 2 rows at a time with all element loads in flight
# speedup vs baseline: 1.0092x; 1.0092x over previous
.LBB0_693:
	v_readlane_b32 s40, v254, 24
	s_andn2_b64 vcc, exec, s[0:1]
	v_readlane_b32 s41, v254, 25
	s_cbranch_vccnz .LBB0_786
	s_waitcnt lgkmcnt(0)
	v_readlane_b32 s2, v254, 8
	v_readlane_b32 s3, v254, 9
	s_mov_b64 s[0:1], -1
	s_and_b64 vcc, exec, s[2:3]
	s_movk_i32 s19, 0xfff
	s_cbranch_vccz .LBB0_767
	v_readlane_b32 s2, v254, 12
	v_readlane_b32 s3, v254, 13
	v_readlane_b32 s50, v254, 22
	s_and_b64 vcc, exec, s[2:3]
	s_movk_i32 s17, 0x4000
	s_mov_b32 s18, 0xbfb8aa3b
	s_movk_i32 s27, 0x1a00
	s_mov_b32 s40, 0x40000
	s_mov_b32 s41, 0x3ffff
	s_mov_b32 s43, 0x100000
	s_mov_b32 s44, 0xfffff
	s_mov_b32 s48, 0x3f317217
	s_mov_b32 s49, 0x7f800000
	v_readlane_b32 s51, v254, 23
	s_cbranch_vccz .LBB0_756
	v_readlane_b32 s2, v254, 14
	v_readlane_b32 s3, v254, 15
	s_and_b64 vcc, exec, s[2:3]
	s_mov_b32 s16, 0xffff
	s_mov_b32 s42, 0x7ffff
	s_mov_b32 s47, 0x7060302
	s_cbranch_vccz .LBB0_720
	v_mov_b32_e32 v1, v0
	v_mov_b32_e32 v2, v0
	s_mov_b32 s0, s87
	v_ashrrev_i32_e32 v2, 6, v2
	s_nop 0
	v_lshl_add_u32 v4, s0, 3, v2
	s_movk_i32 s0, 0x2000
	v_cmp_gt_i32_e32 vcc, s0, v4
	s_and_saveexec_b64 s[0:1], vcc
	s_cbranch_execz .LBB0_711
	v_and_b32_e32 v6, 63, v1
	v_and_b32_e32 v1, 64, v223
	v_add_u32_e32 v5, 64, v1
	v_xor_b32_e32 v1, 32, v223
	v_cmp_lt_i32_e32 vcc, v1, v5
	v_xor_b32_e32 v7, 16, v223
	v_xor_b32_e32 v12, 8, v223
	v_cndmask_b32_e32 v1, v223, v1, vcc
	v_cmp_lt_i32_e32 vcc, v7, v5
	s_load_dword s2, s[20:21], 0x0
	s_load_dwordx2 s[6:7], s[30:31], 0x130
	s_load_dwordx2 s[8:9], s[30:31], 0x148
	v_cndmask_b32_e32 v7, v223, v7, vcc
	v_cmp_lt_i32_e32 vcc, v12, v5
	v_lshlrev_b32_e32 v14, 2, v6
	v_mov_b32_e32 v15, v3
	v_cndmask_b32_e32 v12, v223, v12, vcc
	v_lshlrev_b32_e32 v34, 2, v12
	v_xor_b32_e32 v12, 4, v223
	v_cmp_lt_i32_e32 vcc, v12, v5
	v_lshlrev_b32_e32 v2, 1, v6
	v_lshl_add_u64 v[8:9], s[36:37], 0, v[2:3]
	v_cndmask_b32_e32 v12, v223, v12, vcc
	v_lshlrev_b32_e32 v35, 2, v12
	v_xor_b32_e32 v12, 2, v223
	v_cmp_lt_i32_e32 vcc, v12, v5
	v_lshl_add_u64 v[10:11], s[76:77], 0, v[2:3]
	v_cmp_gt_u32_e64 s[4:5], 32, v6
	v_cndmask_b32_e32 v12, v223, v12, vcc
	v_lshlrev_b32_e32 v37, 2, v12
	v_xor_b32_e32 v12, 1, v223
	v_cmp_lt_i32_e32 vcc, v12, v5
	s_waitcnt lgkmcnt(0)
	s_lshl_b32 s2, s2, 3
	v_lshlrev_b32_e32 v1, 2, v1
	v_cndmask_b32_e32 v5, v223, v12, vcc
	v_lshl_add_u64 v[12:13], s[6:7], 0, v[14:15]
	v_readlane_b32 s6, v254, 20
	v_readlane_b32 s7, v254, 21
	v_lshlrev_b32_e32 v7, 2, v7
	v_lshlrev_b32_e32 v38, 2, v5
	v_lshl_add_u64 v[14:15], s[8:9], 0, v[14:15]
	v_lshl_add_u64 v[16:17], s[34:35], 0, v[2:3]
	v_lshl_add_u64 v[18:19], s[6:7], 0, v[2:3]
	s_mov_b64 s[6:7], 0
	s_cmp_eq_u32 s2, 0x800
	s_cbranch_scc0 .LBB0_700
	v_readfirstlane_b32 s3, v4
	s_cmp_lt_u32 s3, 0x800
	s_cbranch_scc0 .LBB0_700
	s_load_dwordx2 s[10:11], s[30:31], 0x170
	global_load_dword v124, v[12:13], off
	global_load_dword v125, v[12:13], off offset:256
	global_load_dword v126, v[12:13], off offset:512
	global_load_dword v127, v[12:13], off offset:768
	global_load_dword v128, v[12:13], off offset:1024
	global_load_dword v129, v[12:13], off offset:1280
	global_load_dword v130, v[14:15], off
	global_load_dword v131, v[14:15], off offset:256
	global_load_dword v132, v[14:15], off offset:512
	global_load_dword v133, v[14:15], off offset:768
	v_mov_b32_e32 v134, v4
	s_movk_i32 s3, 0x600
	v_mad_i64_i32 v[136:137], s[8:9], v134, s3, v[16:17]
	v_mad_i64_i32 v[142:143], s[8:9], v134, s3, v[18:19]
	global_load_ushort v80, v[136:137], off
	global_load_ushort v81, v[136:137], off offset:128
	global_load_ushort v82, v[136:137], off offset:256
	global_load_ushort v83, v[136:137], off offset:384
	global_load_ushort v84, v[136:137], off offset:512
	global_load_ushort v85, v[136:137], off offset:640
	global_load_ushort v86, v[136:137], off offset:768
	global_load_ushort v87, v[136:137], off offset:896
	global_load_ushort v88, v[136:137], off offset:1024
	global_load_ushort v89, v[136:137], off offset:1152
	global_load_ushort v90, v[136:137], off offset:1280
	global_load_ushort v91, v[142:143], off
	global_load_ushort v92, v[142:143], off offset:128
	global_load_ushort v93, v[142:143], off offset:256
	global_load_ushort v94, v[142:143], off offset:384
	global_load_ushort v95, v[142:143], off offset:512
	global_load_ushort v96, v[142:143], off offset:640
	global_load_ushort v97, v[142:143], off offset:768
	global_load_ushort v98, v[142:143], off offset:896
	global_load_ushort v99, v[142:143], off offset:1024
	global_load_ushort v100, v[142:143], off offset:1152
	global_load_ushort v101, v[142:143], off offset:1280
	v_add_u32_e32 v135, 0x800, v4
	s_movk_i32 s3, 0x600
	v_mad_i64_i32 v[138:139], s[8:9], v135, s3, v[16:17]
	v_mad_i64_i32 v[144:145], s[8:9], v135, s3, v[18:19]
	global_load_ushort v102, v[138:139], off
	global_load_ushort v103, v[138:139], off offset:128
	global_load_ushort v104, v[138:139], off offset:256
	global_load_ushort v105, v[138:139], off offset:384
	global_load_ushort v106, v[138:139], off offset:512
	global_load_ushort v107, v[138:139], off offset:640
	global_load_ushort v108, v[138:139], off offset:768
	global_load_ushort v109, v[138:139], off offset:896
	global_load_ushort v110, v[138:139], off offset:1024
	global_load_ushort v111, v[138:139], off offset:1152
	global_load_ushort v112, v[138:139], off offset:1280
	global_load_ushort v113, v[144:145], off
	global_load_ushort v114, v[144:145], off offset:128
	global_load_ushort v115, v[144:145], off offset:256
	global_load_ushort v116, v[144:145], off offset:384
	global_load_ushort v117, v[144:145], off offset:512
	global_load_ushort v118, v[144:145], off offset:640
	global_load_ushort v119, v[144:145], off offset:768
	global_load_ushort v120, v[144:145], off offset:896
	global_load_ushort v121, v[144:145], off offset:1024
	global_load_ushort v122, v[144:145], off offset:1152
	global_load_ushort v123, v[144:145], off offset:1280
	s_waitcnt vmcnt(0)
	v_add_u32_e32 v248, 0x1000, v4
	s_movk_i32 s3, 0x600
	v_mad_i64_i32 v[250:251], s[8:9], v248, s3, v[16:17]
	v_mad_i64_i32 v[152:153], s[8:9], v248, s3, v[18:19]
	global_load_ushort v188, v[250:251], off
	global_load_ushort v189, v[250:251], off offset:128
	global_load_ushort v190, v[250:251], off offset:256
	global_load_ushort v191, v[250:251], off offset:384
	global_load_ushort v192, v[250:251], off offset:512
	global_load_ushort v193, v[250:251], off offset:640
	global_load_ushort v194, v[250:251], off offset:768
	global_load_ushort v195, v[250:251], off offset:896
	global_load_ushort v196, v[250:251], off offset:1024
	global_load_ushort v197, v[250:251], off offset:1152
	global_load_ushort v198, v[250:251], off offset:1280
	global_load_ushort v199, v[152:153], off
	global_load_ushort v200, v[152:153], off offset:128
	global_load_ushort v201, v[152:153], off offset:256
	global_load_ushort v202, v[152:153], off offset:384
	global_load_ushort v203, v[152:153], off offset:512
	global_load_ushort v204, v[152:153], off offset:640
	global_load_ushort v205, v[152:153], off offset:768
	global_load_ushort v206, v[152:153], off offset:896
	global_load_ushort v207, v[152:153], off offset:1024
	global_load_ushort v208, v[152:153], off offset:1152
	global_load_ushort v209, v[152:153], off offset:1280
	v_add_u32_e32 v249, 0x1800, v4
	s_movk_i32 s3, 0x600
	v_mad_i64_i32 v[252:253], s[8:9], v249, s3, v[16:17]
	v_mad_i64_i32 v[154:155], s[8:9], v249, s3, v[18:19]
	global_load_ushort v210, v[252:253], off
	global_load_ushort v211, v[252:253], off offset:128
	global_load_ushort v212, v[252:253], off offset:256
	global_load_ushort v213, v[252:253], off offset:384
	global_load_ushort v214, v[252:253], off offset:512
	global_load_ushort v215, v[252:253], off offset:640
	global_load_ushort v216, v[252:253], off offset:768
	global_load_ushort v217, v[252:253], off offset:896
	global_load_ushort v234, v[252:253], off offset:1024
	global_load_ushort v235, v[252:253], off offset:1152
	global_load_ushort v236, v[252:253], off offset:1280
	global_load_ushort v237, v[154:155], off
	global_load_ushort v238, v[154:155], off offset:128
	global_load_ushort v239, v[154:155], off offset:256
	global_load_ushort v240, v[154:155], off offset:384
	global_load_ushort v241, v[154:155], off offset:512
	global_load_ushort v242, v[154:155], off offset:640
	global_load_ushort v243, v[154:155], off offset:768
	global_load_ushort v244, v[154:155], off offset:896
	global_load_ushort v245, v[154:155], off offset:1024
	global_load_ushort v246, v[154:155], off offset:1152
	global_load_ushort v247, v[154:155], off offset:1280
	v_lshlrev_b32_e32 v80, 16, v80
	v_lshlrev_b32_e32 v91, 16, v91
	v_add_f32_e32 v80, v80, v91
	v_lshlrev_b32_e32 v81, 16, v81
	v_lshlrev_b32_e32 v92, 16, v92
	v_add_f32_e32 v81, v81, v92
	v_lshlrev_b32_e32 v82, 16, v82
	v_lshlrev_b32_e32 v93, 16, v93
	v_add_f32_e32 v82, v82, v93
	v_lshlrev_b32_e32 v83, 16, v83
	v_lshlrev_b32_e32 v94, 16, v94
	v_add_f32_e32 v83, v83, v94
	v_lshlrev_b32_e32 v84, 16, v84
	v_lshlrev_b32_e32 v95, 16, v95
	v_add_f32_e32 v84, v84, v95
	v_lshlrev_b32_e32 v85, 16, v85
	v_lshlrev_b32_e32 v96, 16, v96
	v_add_f32_e32 v85, v85, v96
	v_lshlrev_b32_e32 v86, 16, v86
	v_lshlrev_b32_e32 v97, 16, v97
	v_add_f32_e32 v86, v86, v97
	v_lshlrev_b32_e32 v87, 16, v87
	v_lshlrev_b32_e32 v98, 16, v98
	v_add_f32_e32 v87, v87, v98
	v_lshlrev_b32_e32 v88, 16, v88
	v_lshlrev_b32_e32 v99, 16, v99
	v_add_f32_e32 v88, v88, v99
	v_lshlrev_b32_e32 v89, 16, v89
	v_lshlrev_b32_e32 v100, 16, v100
	v_add_f32_e32 v89, v89, v100
	v_lshlrev_b32_e32 v90, 16, v90
	v_lshlrev_b32_e32 v101, 16, v101
	v_add_f32_e32 v90, v101, v90
	v_mul_f32_e32 v146, v81, v81
	v_fmac_f32_e32 v146, v80, v80
	v_mul_f32_e32 v147, v82, v82
	v_add_f32_e32 v146, v146, v147
	v_mul_f32_e32 v147, v83, v83
	v_add_f32_e32 v146, v146, v147
	v_mul_f32_e32 v147, v84, v84
	v_add_f32_e32 v146, v146, v147
	v_mul_f32_e32 v147, v85, v85
	v_add_f32_e32 v146, v146, v147
	ds_bpermute_b32 v147, v1, v146
	s_waitcnt lgkmcnt(0)
	v_add_f32_e32 v146, v146, v147
	ds_bpermute_b32 v147, v7, v146
	s_waitcnt lgkmcnt(0)
	v_add_f32_e32 v146, v146, v147
	ds_bpermute_b32 v147, v34, v146
	s_waitcnt lgkmcnt(0)
	v_add_f32_e32 v146, v146, v147
	ds_bpermute_b32 v147, v35, v146
	s_waitcnt lgkmcnt(0)
	v_add_f32_e32 v146, v146, v147
	ds_bpermute_b32 v147, v37, v146
	s_waitcnt lgkmcnt(0)
	v_add_f32_e32 v146, v146, v147
	ds_bpermute_b32 v147, v38, v146
	s_waitcnt lgkmcnt(0)
	v_add_f32_e32 v146, v146, v147
	v_fmamk_f32 v146, v146, 0x3b2aaaab, v218
	v_cmp_gt_f32_e32 vcc, s71, v146
	v_mul_f32_e32 v147, 0x4b800000, v146
	s_nop 0
	v_cndmask_b32_e32 v146, v146, v147, vcc
	v_rsq_f32_e32 v146, v146
	s_nop 0
	v_mul_f32_e32 v147, 0x45800000, v146
	v_cndmask_b32_e32 v146, v146, v147, vcc
	v_mad_i64_i32 v[148:149], s[8:9], v134, s70, v[8:9]
	v_mul_f32_e32 v147, v80, v146
	v_mul_f32_e32 v147, v124, v147
	v_bfe_u32 v150, v147, 16, 1
	v_add3_u32 v147, v147, v150, s73
	global_store_short_d16_hi v[148:149], v147, off
	v_mul_f32_e32 v147, v81, v146
	v_mul_f32_e32 v147, v125, v147
	v_bfe_u32 v150, v147, 16, 1
	v_add3_u32 v147, v147, v150, s73
	global_store_short_d16_hi v[148:149], v147, off offset:128
	v_mul_f32_e32 v147, v82, v146
	v_mul_f32_e32 v147, v126, v147
	v_bfe_u32 v150, v147, 16, 1
	v_add3_u32 v147, v147, v150, s73
	global_store_short_d16_hi v[148:149], v147, off offset:256
	v_mul_f32_e32 v147, v83, v146
	v_mul_f32_e32 v147, v127, v147
	v_bfe_u32 v150, v147, 16, 1
	v_add3_u32 v147, v147, v150, s73
	global_store_short_d16_hi v[148:149], v147, off offset:384
	v_mul_f32_e32 v147, v84, v146
	v_mul_f32_e32 v147, v128, v147
	v_bfe_u32 v150, v147, 16, 1
	v_add3_u32 v147, v147, v150, s73
	global_store_short_d16_hi v[148:149], v147, off offset:512
	v_mul_f32_e32 v147, v85, v146
	v_mul_f32_e32 v147, v129, v147
	v_bfe_u32 v150, v147, 16, 1
	v_add3_u32 v147, v147, v150, s73
	global_store_short_d16_hi v[148:149], v147, off offset:640
	v_mul_f32_e32 v146, v86, v86
	v_mul_f32_e32 v147, v87, v87
	v_add_f32_e32 v146, v146, v147
	v_mul_f32_e32 v147, v88, v88
	v_add_f32_e32 v146, v146, v147
	v_mul_f32_e32 v147, v89, v89
	v_add_f32_e32 v146, v146, v147
	ds_bpermute_b32 v147, v1, v146
	s_waitcnt lgkmcnt(0)
	v_add_f32_e32 v146, v146, v147
	ds_bpermute_b32 v147, v7, v146
	s_waitcnt lgkmcnt(0)
	v_add_f32_e32 v146, v146, v147
	ds_bpermute_b32 v147, v34, v146
	s_waitcnt lgkmcnt(0)
	v_add_f32_e32 v146, v146, v147
	ds_bpermute_b32 v147, v35, v146
	s_waitcnt lgkmcnt(0)
	v_add_f32_e32 v146, v146, v147
	ds_bpermute_b32 v147, v37, v146
	s_waitcnt lgkmcnt(0)
	v_add_f32_e32 v146, v146, v147
	ds_bpermute_b32 v147, v38, v146
	s_waitcnt lgkmcnt(0)
	v_add_f32_e32 v146, v146, v147
	v_fmamk_f32 v146, v146, 0x3b800000, v218
	v_cmp_gt_f32_e32 vcc, s71, v146
	v_mul_f32_e32 v147, 0x4b800000, v146
	s_nop 0
	v_cndmask_b32_e32 v146, v146, v147, vcc
	v_rsq_f32_e32 v146, v146
	s_nop 0
	v_mul_f32_e32 v147, 0x45800000, v146
	v_cndmask_b32_e32 v146, v146, v147, vcc
	v_ashrrev_i32_e32 v151, 31, v134
	v_mov_b32_e32 v150, v134
	v_lshlrev_b64 v[148:149], 9, v[150:151]
	v_lshl_add_u64 v[148:149], v[10:11], 0, v[148:149]
	v_lshlrev_b64 v[152:153], 10, v[150:151]
	s_waitcnt lgkmcnt(0)
	v_lshl_add_u64 v[152:153], s[10:11], 0, v[152:153]
	v_lshlrev_b32_e32 v154, 2, v6
	v_mov_b32_e32 v155, v3
	v_lshl_add_u64 v[154:155], v[152:153], 0, v[154:155]
	s_mov_b64 s[8:9], 0x7000000
	v_lshl_add_u64 v[154:155], v[154:155], 0, s[8:9]
	v_mul_f32_e32 v147, v86, v146
	v_mul_f32_e32 v147, v130, v147
	v_bfe_u32 v150, v147, 16, 1
	v_add3_u32 v150, v147, v150, s73
	global_store_short_d16_hi v[148:149], v150, off
	global_store_dword v[154:155], v147, off
	v_mul_f32_e32 v147, v87, v146
	v_mul_f32_e32 v147, v131, v147
	v_bfe_u32 v150, v147, 16, 1
	v_add3_u32 v150, v147, v150, s73
	global_store_short_d16_hi v[148:149], v150, off offset:128
	global_store_dword v[154:155], v147, off offset:256
	v_mul_f32_e32 v147, v88, v146
	v_mul_f32_e32 v147, v132, v147
	v_bfe_u32 v150, v147, 16, 1
	v_add3_u32 v150, v147, v150, s73
	global_store_short_d16_hi v[148:149], v150, off offset:256
	global_store_dword v[154:155], v147, off offset:512
	v_mul_f32_e32 v147, v89, v146
	v_mul_f32_e32 v147, v133, v147
	v_bfe_u32 v150, v147, 16, 1
	v_add3_u32 v150, v147, v150, s73
	global_store_short_d16_hi v[148:149], v150, off offset:384
	global_store_dword v[154:155], v147, off offset:768
	s_and_saveexec_b64 s[8:9], s[4:5]
	v_bfe_u32 v147, v90, 16, 1
	v_add3_u32 v147, v90, v147, s73
	global_store_short_d16_hi v[136:137], v147, off offset:1280
	s_movk_i32 s3, 0xfc80
	v_mad_i64_i32 v[148:149], s[12:13], v134, s3, v[152:153]
	v_lshlrev_b32_e32 v150, 2, v6
	v_mov_b32_e32 v151, v3
	v_lshl_add_u64 v[148:149], v[148:149], 0, v[150:151]
	v_add_co_u32_e32 v148, vcc, 0x7400000, v148
	s_nop 1
	v_addc_co_u32_e32 v149, vcc, 0, v149, vcc
	global_store_dword v[148:149], v90, off
	s_or_b64 exec, exec, s[8:9]
	v_lshlrev_b32_e32 v102, 16, v102
	v_lshlrev_b32_e32 v113, 16, v113
	v_add_f32_e32 v102, v102, v113
	v_lshlrev_b32_e32 v103, 16, v103
	v_lshlrev_b32_e32 v114, 16, v114
	v_add_f32_e32 v103, v103, v114
	v_lshlrev_b32_e32 v104, 16, v104
	v_lshlrev_b32_e32 v115, 16, v115
	v_add_f32_e32 v104, v104, v115
	v_lshlrev_b32_e32 v105, 16, v105
	v_lshlrev_b32_e32 v116, 16, v116
	v_add_f32_e32 v105, v105, v116
	v_lshlrev_b32_e32 v106, 16, v106
	v_lshlrev_b32_e32 v117, 16, v117
	v_add_f32_e32 v106, v106, v117
	v_lshlrev_b32_e32 v107, 16, v107
	v_lshlrev_b32_e32 v118, 16, v118
	v_add_f32_e32 v107, v107, v118
	v_lshlrev_b32_e32 v108, 16, v108
	v_lshlrev_b32_e32 v119, 16, v119
	v_add_f32_e32 v108, v108, v119
	v_lshlrev_b32_e32 v109, 16, v109
	v_lshlrev_b32_e32 v120, 16, v120
	v_add_f32_e32 v109, v109, v120
	v_lshlrev_b32_e32 v110, 16, v110
	v_lshlrev_b32_e32 v121, 16, v121
	v_add_f32_e32 v110, v110, v121
	v_lshlrev_b32_e32 v111, 16, v111
	v_lshlrev_b32_e32 v122, 16, v122
	v_add_f32_e32 v111, v111, v122
	v_lshlrev_b32_e32 v112, 16, v112
	v_lshlrev_b32_e32 v123, 16, v123
	v_add_f32_e32 v112, v123, v112
	v_mul_f32_e32 v146, v103, v103
	v_fmac_f32_e32 v146, v102, v102
	v_mul_f32_e32 v147, v104, v104
	v_add_f32_e32 v146, v146, v147
	v_mul_f32_e32 v147, v105, v105
	v_add_f32_e32 v146, v146, v147
	v_mul_f32_e32 v147, v106, v106
	v_add_f32_e32 v146, v146, v147
	v_mul_f32_e32 v147, v107, v107
	v_add_f32_e32 v146, v146, v147
	ds_bpermute_b32 v147, v1, v146
	s_waitcnt lgkmcnt(0)
	v_add_f32_e32 v146, v146, v147
	ds_bpermute_b32 v147, v7, v146
	s_waitcnt lgkmcnt(0)
	v_add_f32_e32 v146, v146, v147
	ds_bpermute_b32 v147, v34, v146
	s_waitcnt lgkmcnt(0)
	v_add_f32_e32 v146, v146, v147
	ds_bpermute_b32 v147, v35, v146
	s_waitcnt lgkmcnt(0)
	v_add_f32_e32 v146, v146, v147
	ds_bpermute_b32 v147, v37, v146
	s_waitcnt lgkmcnt(0)
	v_add_f32_e32 v146, v146, v147
	ds_bpermute_b32 v147, v38, v146
	s_waitcnt lgkmcnt(0)
	v_add_f32_e32 v146, v146, v147
	v_fmamk_f32 v146, v146, 0x3b2aaaab, v218
	v_cmp_gt_f32_e32 vcc, s71, v146
	v_mul_f32_e32 v147, 0x4b800000, v146
	s_nop 0
	v_cndmask_b32_e32 v146, v146, v147, vcc
	v_rsq_f32_e32 v146, v146
	s_nop 0
	v_mul_f32_e32 v147, 0x45800000, v146
	v_cndmask_b32_e32 v146, v146, v147, vcc
	v_mad_i64_i32 v[148:149], s[8:9], v135, s70, v[8:9]
	v_mul_f32_e32 v147, v102, v146
	v_mul_f32_e32 v147, v124, v147
	v_bfe_u32 v150, v147, 16, 1
	v_add3_u32 v147, v147, v150, s73
	global_store_short_d16_hi v[148:149], v147, off
	v_mul_f32_e32 v147, v103, v146
	v_mul_f32_e32 v147, v125, v147
	v_bfe_u32 v150, v147, 16, 1
	v_add3_u32 v147, v147, v150, s73
	global_store_short_d16_hi v[148:149], v147, off offset:128
	v_mul_f32_e32 v147, v104, v146
	v_mul_f32_e32 v147, v126, v147
	v_bfe_u32 v150, v147, 16, 1
	v_add3_u32 v147, v147, v150, s73
	global_store_short_d16_hi v[148:149], v147, off offset:256
	v_mul_f32_e32 v147, v105, v146
	v_mul_f32_e32 v147, v127, v147
	v_bfe_u32 v150, v147, 16, 1
	v_add3_u32 v147, v147, v150, s73
	global_store_short_d16_hi v[148:149], v147, off offset:384
	v_mul_f32_e32 v147, v106, v146
	v_mul_f32_e32 v147, v128, v147
	v_bfe_u32 v150, v147, 16, 1
	v_add3_u32 v147, v147, v150, s73
	global_store_short_d16_hi v[148:149], v147, off offset:512
	v_mul_f32_e32 v147, v107, v146
	v_mul_f32_e32 v147, v129, v147
	v_bfe_u32 v150, v147, 16, 1
	v_add3_u32 v147, v147, v150, s73
	global_store_short_d16_hi v[148:149], v147, off offset:640
	v_mul_f32_e32 v146, v108, v108
	v_mul_f32_e32 v147, v109, v109
	v_add_f32_e32 v146, v146, v147
	v_mul_f32_e32 v147, v110, v110
	v_add_f32_e32 v146, v146, v147
	v_mul_f32_e32 v147, v111, v111
	v_add_f32_e32 v146, v146, v147
	ds_bpermute_b32 v147, v1, v146
	s_waitcnt lgkmcnt(0)
	v_add_f32_e32 v146, v146, v147
	ds_bpermute_b32 v147, v7, v146
	s_waitcnt lgkmcnt(0)
	v_add_f32_e32 v146, v146, v147
	ds_bpermute_b32 v147, v34, v146
	s_waitcnt lgkmcnt(0)
	v_add_f32_e32 v146, v146, v147
	ds_bpermute_b32 v147, v35, v146
	s_waitcnt lgkmcnt(0)
	v_add_f32_e32 v146, v146, v147
	ds_bpermute_b32 v147, v37, v146
	s_waitcnt lgkmcnt(0)
	v_add_f32_e32 v146, v146, v147
	ds_bpermute_b32 v147, v38, v146
	s_waitcnt lgkmcnt(0)
	v_add_f32_e32 v146, v146, v147
	v_fmamk_f32 v146, v146, 0x3b800000, v218
	v_cmp_gt_f32_e32 vcc, s71, v146
	v_mul_f32_e32 v147, 0x4b800000, v146
	s_nop 0
	v_cndmask_b32_e32 v146, v146, v147, vcc
	v_rsq_f32_e32 v146, v146
	s_nop 0
	v_mul_f32_e32 v147, 0x45800000, v146
	v_cndmask_b32_e32 v146, v146, v147, vcc
	v_ashrrev_i32_e32 v151, 31, v135
	v_mov_b32_e32 v150, v135
	v_lshlrev_b64 v[148:149], 9, v[150:151]
	v_lshl_add_u64 v[148:149], v[10:11], 0, v[148:149]
	v_lshlrev_b64 v[152:153], 10, v[150:151]
	s_waitcnt lgkmcnt(0)
	v_lshl_add_u64 v[152:153], s[10:11], 0, v[152:153]
	v_lshlrev_b32_e32 v154, 2, v6
	v_mov_b32_e32 v155, v3
	v_lshl_add_u64 v[154:155], v[152:153], 0, v[154:155]
	s_mov_b64 s[8:9], 0x7000000
	v_lshl_add_u64 v[154:155], v[154:155], 0, s[8:9]
	v_mul_f32_e32 v147, v108, v146
	v_mul_f32_e32 v147, v130, v147
	v_bfe_u32 v150, v147, 16, 1
	v_add3_u32 v150, v147, v150, s73
	global_store_short_d16_hi v[148:149], v150, off
	global_store_dword v[154:155], v147, off
	v_mul_f32_e32 v147, v109, v146
	v_mul_f32_e32 v147, v131, v147
	v_bfe_u32 v150, v147, 16, 1
	v_add3_u32 v150, v147, v150, s73
	global_store_short_d16_hi v[148:149], v150, off offset:128
	global_store_dword v[154:155], v147, off offset:256
	v_mul_f32_e32 v147, v110, v146
	v_mul_f32_e32 v147, v132, v147
	v_bfe_u32 v150, v147, 16, 1
	v_add3_u32 v150, v147, v150, s73
	global_store_short_d16_hi v[148:149], v150, off offset:256
	global_store_dword v[154:155], v147, off offset:512
	v_mul_f32_e32 v147, v111, v146
	v_mul_f32_e32 v147, v133, v147
	v_bfe_u32 v150, v147, 16, 1
	v_add3_u32 v150, v147, v150, s73
	global_store_short_d16_hi v[148:149], v150, off offset:384
	global_store_dword v[154:155], v147, off offset:768
	s_and_saveexec_b64 s[8:9], s[4:5]
	v_bfe_u32 v147, v112, 16, 1
	v_add3_u32 v147, v112, v147, s73
	global_store_short_d16_hi v[138:139], v147, off offset:1280
	s_movk_i32 s3, 0xfc80
	v_mad_i64_i32 v[148:149], s[12:13], v135, s3, v[152:153]
	v_lshlrev_b32_e32 v150, 2, v6
	v_mov_b32_e32 v151, v3
	v_lshl_add_u64 v[148:149], v[148:149], 0, v[150:151]
	v_add_co_u32_e32 v148, vcc, 0x7400000, v148
	s_nop 1
	v_addc_co_u32_e32 v149, vcc, 0, v149, vcc
	global_store_dword v[148:149], v112, off
	s_or_b64 exec, exec, s[8:9]
	s_waitcnt vmcnt(0)
	v_lshlrev_b32_e32 v188, 16, v188
	v_lshlrev_b32_e32 v199, 16, v199
	v_add_f32_e32 v188, v188, v199
	v_lshlrev_b32_e32 v189, 16, v189
	v_lshlrev_b32_e32 v200, 16, v200
	v_add_f32_e32 v189, v189, v200
	v_lshlrev_b32_e32 v190, 16, v190
	v_lshlrev_b32_e32 v201, 16, v201
	v_add_f32_e32 v190, v190, v201
	v_lshlrev_b32_e32 v191, 16, v191
	v_lshlrev_b32_e32 v202, 16, v202
	v_add_f32_e32 v191, v191, v202
	v_lshlrev_b32_e32 v192, 16, v192
	v_lshlrev_b32_e32 v203, 16, v203
	v_add_f32_e32 v192, v192, v203
	v_lshlrev_b32_e32 v193, 16, v193
	v_lshlrev_b32_e32 v204, 16, v204
	v_add_f32_e32 v193, v193, v204
	v_lshlrev_b32_e32 v194, 16, v194
	v_lshlrev_b32_e32 v205, 16, v205
	v_add_f32_e32 v194, v194, v205
	v_lshlrev_b32_e32 v195, 16, v195
	v_lshlrev_b32_e32 v206, 16, v206
	v_add_f32_e32 v195, v195, v206
	v_lshlrev_b32_e32 v196, 16, v196
	v_lshlrev_b32_e32 v207, 16, v207
	v_add_f32_e32 v196, v196, v207
	v_lshlrev_b32_e32 v197, 16, v197
	v_lshlrev_b32_e32 v208, 16, v208
	v_add_f32_e32 v197, v197, v208
	v_lshlrev_b32_e32 v198, 16, v198
	v_lshlrev_b32_e32 v209, 16, v209
	v_add_f32_e32 v198, v209, v198
	v_mul_f32_e32 v146, v189, v189
	v_fmac_f32_e32 v146, v188, v188
	v_mul_f32_e32 v147, v190, v190
	v_add_f32_e32 v146, v146, v147
	v_mul_f32_e32 v147, v191, v191
	v_add_f32_e32 v146, v146, v147
	v_mul_f32_e32 v147, v192, v192
	v_add_f32_e32 v146, v146, v147
	v_mul_f32_e32 v147, v193, v193
	v_add_f32_e32 v146, v146, v147
	ds_bpermute_b32 v147, v1, v146
	s_waitcnt lgkmcnt(0)
	v_add_f32_e32 v146, v146, v147
	ds_bpermute_b32 v147, v7, v146
	s_waitcnt lgkmcnt(0)
	v_add_f32_e32 v146, v146, v147
	ds_bpermute_b32 v147, v34, v146
	s_waitcnt lgkmcnt(0)
	v_add_f32_e32 v146, v146, v147
	ds_bpermute_b32 v147, v35, v146
	s_waitcnt lgkmcnt(0)
	v_add_f32_e32 v146, v146, v147
	ds_bpermute_b32 v147, v37, v146
	s_waitcnt lgkmcnt(0)
	v_add_f32_e32 v146, v146, v147
	ds_bpermute_b32 v147, v38, v146
	s_waitcnt lgkmcnt(0)
	v_add_f32_e32 v146, v146, v147
	v_fmamk_f32 v146, v146, 0x3b2aaaab, v218
	v_cmp_gt_f32_e32 vcc, s71, v146
	v_mul_f32_e32 v147, 0x4b800000, v146
	s_nop 0
	v_cndmask_b32_e32 v146, v146, v147, vcc
	v_rsq_f32_e32 v146, v146
	s_nop 0
	v_mul_f32_e32 v147, 0x45800000, v146
	v_cndmask_b32_e32 v146, v146, v147, vcc
	v_mad_i64_i32 v[148:149], s[8:9], v248, s70, v[8:9]
	v_mul_f32_e32 v147, v188, v146
	v_mul_f32_e32 v147, v124, v147
	v_bfe_u32 v150, v147, 16, 1
	v_add3_u32 v147, v147, v150, s73
	global_store_short_d16_hi v[148:149], v147, off
	v_mul_f32_e32 v147, v189, v146
	v_mul_f32_e32 v147, v125, v147
	v_bfe_u32 v150, v147, 16, 1
	v_add3_u32 v147, v147, v150, s73
	global_store_short_d16_hi v[148:149], v147, off offset:128
	v_mul_f32_e32 v147, v190, v146
	v_mul_f32_e32 v147, v126, v147
	v_bfe_u32 v150, v147, 16, 1
	v_add3_u32 v147, v147, v150, s73
	global_store_short_d16_hi v[148:149], v147, off offset:256
	v_mul_f32_e32 v147, v191, v146
	v_mul_f32_e32 v147, v127, v147
	v_bfe_u32 v150, v147, 16, 1
	v_add3_u32 v147, v147, v150, s73
	global_store_short_d16_hi v[148:149], v147, off offset:384
	v_mul_f32_e32 v147, v192, v146
	v_mul_f32_e32 v147, v128, v147
	v_bfe_u32 v150, v147, 16, 1
	v_add3_u32 v147, v147, v150, s73
	global_store_short_d16_hi v[148:149], v147, off offset:512
	v_mul_f32_e32 v147, v193, v146
	v_mul_f32_e32 v147, v129, v147
	v_bfe_u32 v150, v147, 16, 1
	v_add3_u32 v147, v147, v150, s73
	global_store_short_d16_hi v[148:149], v147, off offset:640
	v_mul_f32_e32 v146, v194, v194
	v_mul_f32_e32 v147, v195, v195
	v_add_f32_e32 v146, v146, v147
	v_mul_f32_e32 v147, v196, v196
	v_add_f32_e32 v146, v146, v147
	v_mul_f32_e32 v147, v197, v197
	v_add_f32_e32 v146, v146, v147
	ds_bpermute_b32 v147, v1, v146
	s_waitcnt lgkmcnt(0)
	v_add_f32_e32 v146, v146, v147
	ds_bpermute_b32 v147, v7, v146
	s_waitcnt lgkmcnt(0)
	v_add_f32_e32 v146, v146, v147
	ds_bpermute_b32 v147, v34, v146
	s_waitcnt lgkmcnt(0)
	v_add_f32_e32 v146, v146, v147
	ds_bpermute_b32 v147, v35, v146
	s_waitcnt lgkmcnt(0)
	v_add_f32_e32 v146, v146, v147
	ds_bpermute_b32 v147, v37, v146
	s_waitcnt lgkmcnt(0)
	v_add_f32_e32 v146, v146, v147
	ds_bpermute_b32 v147, v38, v146
	s_waitcnt lgkmcnt(0)
	v_add_f32_e32 v146, v146, v147
	v_fmamk_f32 v146, v146, 0x3b800000, v218
	v_cmp_gt_f32_e32 vcc, s71, v146
	v_mul_f32_e32 v147, 0x4b800000, v146
	s_nop 0
	v_cndmask_b32_e32 v146, v146, v147, vcc
	v_rsq_f32_e32 v146, v146
	s_nop 0
	v_mul_f32_e32 v147, 0x45800000, v146
	v_cndmask_b32_e32 v146, v146, v147, vcc
	v_ashrrev_i32_e32 v151, 31, v248
	v_mov_b32_e32 v150, v248
	v_lshlrev_b64 v[148:149], 9, v[150:151]
	v_lshl_add_u64 v[148:149], v[10:11], 0, v[148:149]
	v_mul_f32_e32 v147, v194, v146
	v_mul_f32_e32 v147, v130, v147
	v_bfe_u32 v150, v147, 16, 1
	v_add3_u32 v150, v147, v150, s73
	global_store_short_d16_hi v[148:149], v150, off
	v_mul_f32_e32 v147, v195, v146
	v_mul_f32_e32 v147, v131, v147
	v_bfe_u32 v150, v147, 16, 1
	v_add3_u32 v150, v147, v150, s73
	global_store_short_d16_hi v[148:149], v150, off offset:128
	v_mul_f32_e32 v147, v196, v146
	v_mul_f32_e32 v147, v132, v147
	v_bfe_u32 v150, v147, 16, 1
	v_add3_u32 v150, v147, v150, s73
	global_store_short_d16_hi v[148:149], v150, off offset:256
	v_mul_f32_e32 v147, v197, v146
	v_mul_f32_e32 v147, v133, v147
	v_bfe_u32 v150, v147, 16, 1
	v_add3_u32 v150, v147, v150, s73
	global_store_short_d16_hi v[148:149], v150, off offset:384
	s_and_saveexec_b64 s[8:9], s[4:5]
	v_bfe_u32 v147, v198, 16, 1
	v_add3_u32 v147, v198, v147, s73
	global_store_short_d16_hi v[250:251], v147, off offset:1280
	s_or_b64 exec, exec, s[8:9]
	v_lshlrev_b32_e32 v210, 16, v210
	v_lshlrev_b32_e32 v237, 16, v237
	v_add_f32_e32 v210, v210, v237
	v_lshlrev_b32_e32 v211, 16, v211
	v_lshlrev_b32_e32 v238, 16, v238
	v_add_f32_e32 v211, v211, v238
	v_lshlrev_b32_e32 v212, 16, v212
	v_lshlrev_b32_e32 v239, 16, v239
	v_add_f32_e32 v212, v212, v239
	v_lshlrev_b32_e32 v213, 16, v213
	v_lshlrev_b32_e32 v240, 16, v240
	v_add_f32_e32 v213, v213, v240
	v_lshlrev_b32_e32 v214, 16, v214
	v_lshlrev_b32_e32 v241, 16, v241
	v_add_f32_e32 v214, v214, v241
	v_lshlrev_b32_e32 v215, 16, v215
	v_lshlrev_b32_e32 v242, 16, v242
	v_add_f32_e32 v215, v215, v242
	v_lshlrev_b32_e32 v216, 16, v216
	v_lshlrev_b32_e32 v243, 16, v243
	v_add_f32_e32 v216, v216, v243
	v_lshlrev_b32_e32 v217, 16, v217
	v_lshlrev_b32_e32 v244, 16, v244
	v_add_f32_e32 v217, v217, v244
	v_lshlrev_b32_e32 v234, 16, v234
	v_lshlrev_b32_e32 v245, 16, v245
	v_add_f32_e32 v234, v234, v245
	v_lshlrev_b32_e32 v235, 16, v235
	v_lshlrev_b32_e32 v246, 16, v246
	v_add_f32_e32 v235, v235, v246
	v_lshlrev_b32_e32 v236, 16, v236
	v_lshlrev_b32_e32 v247, 16, v247
	v_add_f32_e32 v236, v247, v236
	v_mul_f32_e32 v146, v211, v211
	v_fmac_f32_e32 v146, v210, v210
	v_mul_f32_e32 v147, v212, v212
	v_add_f32_e32 v146, v146, v147
	v_mul_f32_e32 v147, v213, v213
	v_add_f32_e32 v146, v146, v147
	v_mul_f32_e32 v147, v214, v214
	v_add_f32_e32 v146, v146, v147
	v_mul_f32_e32 v147, v215, v215
	v_add_f32_e32 v146, v146, v147
	ds_bpermute_b32 v147, v1, v146
	s_waitcnt lgkmcnt(0)
	v_add_f32_e32 v146, v146, v147
	ds_bpermute_b32 v147, v7, v146
	s_waitcnt lgkmcnt(0)
	v_add_f32_e32 v146, v146, v147
	ds_bpermute_b32 v147, v34, v146
	s_waitcnt lgkmcnt(0)
	v_add_f32_e32 v146, v146, v147
	ds_bpermute_b32 v147, v35, v146
	s_waitcnt lgkmcnt(0)
	v_add_f32_e32 v146, v146, v147
	ds_bpermute_b32 v147, v37, v146
	s_waitcnt lgkmcnt(0)
	v_add_f32_e32 v146, v146, v147
	ds_bpermute_b32 v147, v38, v146
	s_waitcnt lgkmcnt(0)
	v_add_f32_e32 v146, v146, v147
	v_fmamk_f32 v146, v146, 0x3b2aaaab, v218
	v_cmp_gt_f32_e32 vcc, s71, v146
	v_mul_f32_e32 v147, 0x4b800000, v146
	s_nop 0
	v_cndmask_b32_e32 v146, v146, v147, vcc
	v_rsq_f32_e32 v146, v146
	s_nop 0
	v_mul_f32_e32 v147, 0x45800000, v146
	v_cndmask_b32_e32 v146, v146, v147, vcc
	v_mad_i64_i32 v[148:149], s[8:9], v249, s70, v[8:9]
	v_mul_f32_e32 v147, v210, v146
	v_mul_f32_e32 v147, v124, v147
	v_bfe_u32 v150, v147, 16, 1
	v_add3_u32 v147, v147, v150, s73
	global_store_short_d16_hi v[148:149], v147, off
	v_mul_f32_e32 v147, v211, v146
	v_mul_f32_e32 v147, v125, v147
	v_bfe_u32 v150, v147, 16, 1
	v_add3_u32 v147, v147, v150, s73
	global_store_short_d16_hi v[148:149], v147, off offset:128
	v_mul_f32_e32 v147, v212, v146
	v_mul_f32_e32 v147, v126, v147
	v_bfe_u32 v150, v147, 16, 1
	v_add3_u32 v147, v147, v150, s73
	global_store_short_d16_hi v[148:149], v147, off offset:256
	v_mul_f32_e32 v147, v213, v146
	v_mul_f32_e32 v147, v127, v147
	v_bfe_u32 v150, v147, 16, 1
	v_add3_u32 v147, v147, v150, s73
	global_store_short_d16_hi v[148:149], v147, off offset:384
	v_mul_f32_e32 v147, v214, v146
	v_mul_f32_e32 v147, v128, v147
	v_bfe_u32 v150, v147, 16, 1
	v_add3_u32 v147, v147, v150, s73
	global_store_short_d16_hi v[148:149], v147, off offset:512
	v_mul_f32_e32 v147, v215, v146
	v_mul_f32_e32 v147, v129, v147
	v_bfe_u32 v150, v147, 16, 1
	v_add3_u32 v147, v147, v150, s73
	global_store_short_d16_hi v[148:149], v147, off offset:640
	v_mul_f32_e32 v146, v216, v216
	v_mul_f32_e32 v147, v217, v217
	v_add_f32_e32 v146, v146, v147
	v_mul_f32_e32 v147, v234, v234
	v_add_f32_e32 v146, v146, v147
	v_mul_f32_e32 v147, v235, v235
	v_add_f32_e32 v146, v146, v147
	ds_bpermute_b32 v147, v1, v146
	s_waitcnt lgkmcnt(0)
	v_add_f32_e32 v146, v146, v147
	ds_bpermute_b32 v147, v7, v146
	s_waitcnt lgkmcnt(0)
	v_add_f32_e32 v146, v146, v147
	ds_bpermute_b32 v147, v34, v146
	s_waitcnt lgkmcnt(0)
	v_add_f32_e32 v146, v146, v147
	ds_bpermute_b32 v147, v35, v146
	s_waitcnt lgkmcnt(0)
	v_add_f32_e32 v146, v146, v147
	ds_bpermute_b32 v147, v37, v146
	s_waitcnt lgkmcnt(0)
	v_add_f32_e32 v146, v146, v147
	ds_bpermute_b32 v147, v38, v146
	s_waitcnt lgkmcnt(0)
	v_add_f32_e32 v146, v146, v147
	v_fmamk_f32 v146, v146, 0x3b800000, v218
	v_cmp_gt_f32_e32 vcc, s71, v146
	v_mul_f32_e32 v147, 0x4b800000, v146
	s_nop 0
	v_cndmask_b32_e32 v146, v146, v147, vcc
	v_rsq_f32_e32 v146, v146
	s_nop 0
	v_mul_f32_e32 v147, 0x45800000, v146
	v_cndmask_b32_e32 v146, v146, v147, vcc
	v_ashrrev_i32_e32 v151, 31, v249
	v_mov_b32_e32 v150, v249
	v_lshlrev_b64 v[148:149], 9, v[150:151]
	v_lshl_add_u64 v[148:149], v[10:11], 0, v[148:149]
	v_mul_f32_e32 v147, v216, v146
	v_mul_f32_e32 v147, v130, v147
	v_bfe_u32 v150, v147, 16, 1
	v_add3_u32 v150, v147, v150, s73
	global_store_short_d16_hi v[148:149], v150, off
	v_mul_f32_e32 v147, v217, v146
	v_mul_f32_e32 v147, v131, v147
	v_bfe_u32 v150, v147, 16, 1
	v_add3_u32 v150, v147, v150, s73
	global_store_short_d16_hi v[148:149], v150, off offset:128
	v_mul_f32_e32 v147, v234, v146
	v_mul_f32_e32 v147, v132, v147
	v_bfe_u32 v150, v147, 16, 1
	v_add3_u32 v150, v147, v150, s73
	global_store_short_d16_hi v[148:149], v150, off offset:256
	v_mul_f32_e32 v147, v235, v146
	v_mul_f32_e32 v147, v133, v147
	v_bfe_u32 v150, v147, 16, 1
	v_add3_u32 v150, v147, v150, s73
	global_store_short_d16_hi v[148:149], v150, off offset:384
	s_and_saveexec_b64 s[8:9], s[4:5]
	v_bfe_u32 v147, v236, 16, 1
	v_add3_u32 v147, v236, v147, s73
	global_store_short_d16_hi v[252:253], v147, off offset:1280
	s_or_b64 exec, exec, s[8:9]
	s_branch .LBB0_711
